# P0 weight reads marked nt (read-once stream)
# speedup vs baseline: 1.0092x; 1.0092x over previous
; __device__ __forceinline__ void p0_load(const P0Desc& d, f32x4 (&tv)[8]) {
; #pragma unroll
;     for (int i = 0; i < 8; ++i) tv[i] = d.ok ? *(const f32x4*)(d.src + (size_t)i * d.ldw) : (f32x4){0.f, 0.f, 0.f, 0.f};
; }
.LBB0_64:
	v_mov_b32_e32 v27, 0
	v_cndmask_b32_e64 v0, 0, 1, s[22:23]
	v_cmp_ne_u32_e64 s[6:7], 1, v0
	s_andn2_b64 vcc, exec, s[22:23]
	v_mov_b32_e32 v26, v27
	v_mov_b32_e32 v25, v27
	v_mov_b32_e32 v24, v27
	v_mov_b32_e32 v31, v27
	v_mov_b32_e32 v30, v27
	v_mov_b32_e32 v29, v27
	v_mov_b32_e32 v28, v27
	v_mov_b32_e32 v23, v27
	v_mov_b32_e32 v22, v27
	v_mov_b32_e32 v21, v27
	v_mov_b32_e32 v20, v27
	v_mov_b32_e32 v19, v27
	v_mov_b32_e32 v18, v27
	v_mov_b32_e32 v17, v27
	v_mov_b32_e32 v16, v27
	v_mov_b32_e32 v15, v27
	v_mov_b32_e32 v14, v27
	v_mov_b32_e32 v13, v27
	v_mov_b32_e32 v12, v27
	v_mov_b32_e32 v11, v27
	v_mov_b32_e32 v10, v27
	v_mov_b32_e32 v9, v27
	v_mov_b32_e32 v8, v27
	v_mov_b32_e32 v3, v27
	v_mov_b32_e32 v2, v27
	v_mov_b32_e32 v1, v27
	v_mov_b32_e32 v0, v27
	v_mov_b32_e32 v7, v27
	v_mov_b32_e32 v6, v27
	v_mov_b32_e32 v5, v27
	v_mov_b32_e32 v4, v27
	s_cbranch_vccnz .LBB0_82
	v_mov_b32_e32 v0, 0
	v_mov_b32_e32 v4, 0
	v_mov_b32_e32 v5, 0
	v_mov_b32_e32 v6, 0
	v_mov_b32_e32 v7, 0
	s_and_saveexec_b64 s[22:23], s[28:29]
	s_cbranch_execz .LBB0_67
	global_load_dwordx4 v[4:7], v[34:35], off nt
.LBB0_67:
	s_or_b64 exec, exec, s[22:23]
	v_mov_b32_e32 v1, 0
	v_mov_b32_e32 v2, 0
	v_mov_b32_e32 v3, 0
	s_and_saveexec_b64 s[22:23], s[28:29]
	s_cbranch_execz .LBB0_69
	v_lshl_add_u64 v[0:1], s[24:25], 2, v[34:35]
	global_load_dwordx4 v[0:3], v[0:1], off nt
.LBB0_69:
	s_or_b64 exec, exec, s[22:23]
	v_mov_b32_e32 v12, 0
	v_mov_b32_e32 v8, 0
	v_mov_b32_e32 v9, 0
	v_mov_b32_e32 v10, 0
	v_mov_b32_e32 v11, 0
	s_and_saveexec_b64 s[22:23], s[28:29]
	s_cbranch_execz .LBB0_71
	v_lshl_add_u64 v[8:9], s[24:25], 3, v[34:35]
	global_load_dwordx4 v[8:11], v[8:9], off nt
.LBB0_71:
	s_or_b64 exec, exec, s[22:23]
	v_mov_b32_e32 v13, 0
	v_mov_b32_e32 v14, 0
	v_mov_b32_e32 v15, 0
	s_and_saveexec_b64 s[22:23], s[28:29]
	s_cbranch_execz .LBB0_73
	v_mad_u64_u32 v[12:13], s[30:31], s24, 12, v[34:35]
	v_mov_b32_e32 v14, v13
	v_mad_u64_u32 v[14:15], s[30:31], s25, 12, v[14:15]
	v_mov_b32_e32 v13, v14
	global_load_dwordx4 v[12:15], v[12:13], off nt
.LBB0_73:
	s_or_b64 exec, exec, s[22:23]
	v_mov_b32_e32 v20, 0
	v_mov_b32_e32 v16, 0
	v_mov_b32_e32 v17, 0
	v_mov_b32_e32 v18, 0
	v_mov_b32_e32 v19, 0
	s_and_saveexec_b64 s[22:23], s[28:29]
	s_cbranch_execz .LBB0_75
	v_lshl_add_u64 v[16:17], s[24:25], 4, v[34:35]
	global_load_dwordx4 v[16:19], v[16:17], off nt
.LBB0_75:
	s_or_b64 exec, exec, s[22:23]
	v_mov_b32_e32 v21, 0
	v_mov_b32_e32 v22, 0
	v_mov_b32_e32 v23, 0
	s_and_saveexec_b64 s[22:23], s[28:29]
	s_cbranch_execz .LBB0_77
	v_mad_u64_u32 v[20:21], s[30:31], s24, 20, v[34:35]
	v_mov_b32_e32 v22, v21
	v_mad_u64_u32 v[22:23], s[30:31], s25, 20, v[22:23]
	v_mov_b32_e32 v21, v22
	global_load_dwordx4 v[20:23], v[20:21], off nt
.LBB0_77:
	s_or_b64 exec, exec, s[22:23]
	v_mov_b32_e32 v24, 0
	v_mov_b32_e32 v28, 0
	v_mov_b32_e32 v29, 0
	v_mov_b32_e32 v30, 0
	v_mov_b32_e32 v31, 0
	s_and_saveexec_b64 s[22:23], s[28:29]
	s_cbranch_execz .LBB0_79
	v_mad_u64_u32 v[26:27], s[30:31], s24, 24, v[34:35]
	v_mov_b32_e32 v28, v27
	v_mad_u64_u32 v[28:29], s[30:31], s25, 24, v[28:29]
	v_mov_b32_e32 v27, v28
	global_load_dwordx4 v[28:31], v[26:27], off nt
.LBB0_79:
	s_or_b64 exec, exec, s[22:23]
	v_mov_b32_e32 v25, 0
	v_mov_b32_e32 v26, 0
	v_mov_b32_e32 v27, 0
	s_and_saveexec_b64 s[22:23], s[28:29]
	s_cbranch_execz .LBB0_81
	v_mad_u64_u32 v[24:25], s[28:29], s24, 28, v[34:35]
	v_mov_b32_e32 v26, v25
	v_mad_u64_u32 v[26:27], s[24:25], s25, 28, v[26:27]
	v_mov_b32_e32 v25, v26
	global_load_dwordx4 v[24:27], v[24:25], off nt

; __device__ __forceinline__ void p0_load(const P0Desc& d, f32x4 (&tv)[8]) {
; #pragma unroll
;     for (int i = 0; i < 8; ++i) tv[i] = d.ok ? *(const f32x4*)(d.src + (size_t)i * d.ldw) : (f32x4){0.f, 0.f, 0.f, 0.f};
; }
.LBB0_127:
	s_andn2_b64 vcc, exec, s[36:37]
	s_cbranch_vccnz .LBB0_85
	v_mov_b32_e32 v0, 0
	v_mov_b32_e32 v4, 0
	v_mov_b32_e32 v5, 0
	v_mov_b32_e32 v6, 0
	v_mov_b32_e32 v7, 0
	s_and_saveexec_b64 s[36:37], s[30:31]
	s_cbranch_execz .LBB0_130
	global_load_dwordx4 v[4:7], v[44:45], off nt
.LBB0_130:
	s_or_b64 exec, exec, s[36:37]
	v_mov_b32_e32 v1, 0
	v_mov_b32_e32 v2, 0
	v_mov_b32_e32 v3, 0
	s_and_saveexec_b64 s[36:37], s[30:31]
	s_cbranch_execz .LBB0_132
	v_lshl_add_u64 v[0:1], s[22:23], 2, v[44:45]
	global_load_dwordx4 v[0:3], v[0:1], off nt
.LBB0_132:
	s_or_b64 exec, exec, s[36:37]
	v_mov_b32_e32 v12, 0
	v_mov_b32_e32 v8, 0
	v_mov_b32_e32 v9, 0
	v_mov_b32_e32 v10, 0
	v_mov_b32_e32 v11, 0
	s_and_saveexec_b64 s[36:37], s[30:31]
	s_cbranch_execz .LBB0_134
	v_lshl_add_u64 v[8:9], s[22:23], 3, v[44:45]
	global_load_dwordx4 v[8:11], v[8:9], off nt
.LBB0_134:
	s_or_b64 exec, exec, s[36:37]
	v_mov_b32_e32 v13, 0
	v_mov_b32_e32 v14, 0
	v_mov_b32_e32 v15, 0
	s_and_saveexec_b64 s[36:37], s[30:31]
	s_cbranch_execz .LBB0_136
	v_mad_u64_u32 v[12:13], s[38:39], s22, 12, v[44:45]
	v_mov_b32_e32 v14, v13
	v_mad_u64_u32 v[14:15], s[38:39], s23, 12, v[14:15]
	v_mov_b32_e32 v13, v14
	global_load_dwordx4 v[12:15], v[12:13], off nt
.LBB0_136:
	s_or_b64 exec, exec, s[36:37]
	v_mov_b32_e32 v20, 0
	v_mov_b32_e32 v16, 0
	v_mov_b32_e32 v17, 0
	v_mov_b32_e32 v18, 0
	v_mov_b32_e32 v19, 0
	s_and_saveexec_b64 s[36:37], s[30:31]
	s_cbranch_execz .LBB0_138
	v_lshl_add_u64 v[16:17], s[22:23], 4, v[44:45]
	global_load_dwordx4 v[16:19], v[16:17], off nt
.LBB0_138:
	s_or_b64 exec, exec, s[36:37]
	v_mov_b32_e32 v21, 0
	v_mov_b32_e32 v22, 0
	v_mov_b32_e32 v23, 0
	s_and_saveexec_b64 s[36:37], s[30:31]
	s_cbranch_execz .LBB0_140
	v_mad_u64_u32 v[20:21], s[38:39], s22, 20, v[44:45]
	v_mov_b32_e32 v22, v21
	v_mad_u64_u32 v[22:23], s[38:39], s23, 20, v[22:23]
	v_mov_b32_e32 v21, v22
	global_load_dwordx4 v[20:23], v[20:21], off nt
.LBB0_140:
	s_or_b64 exec, exec, s[36:37]
	v_mov_b32_e32 v24, 0
	v_mov_b32_e32 v28, 0
	v_mov_b32_e32 v29, 0
	v_mov_b32_e32 v30, 0
	v_mov_b32_e32 v31, 0
	s_and_saveexec_b64 s[36:37], s[30:31]
	s_cbranch_execz .LBB0_142
	v_mad_u64_u32 v[26:27], s[38:39], s22, 24, v[44:45]
	v_mov_b32_e32 v28, v27
	v_mad_u64_u32 v[28:29], s[38:39], s23, 24, v[28:29]
	v_mov_b32_e32 v27, v28
	global_load_dwordx4 v[28:31], v[26:27], off nt
.LBB0_142:
	s_or_b64 exec, exec, s[36:37]
	v_mov_b32_e32 v25, 0
	v_mov_b32_e32 v26, 0
	v_mov_b32_e32 v27, 0
	s_and_saveexec_b64 s[36:37], s[30:31]
	s_cbranch_execz .LBB0_84
	v_mad_u64_u32 v[24:25], s[38:39], s22, 28, v[44:45]
	v_mov_b32_e32 v26, v25
	v_mad_u64_u32 v[26:27], s[38:39], s23, 28, v[26:27]
	v_mov_b32_e32 v25, v26
	global_load_dwordx4 v[24:27], v[24:25], off nt
	s_branch .LBB0_84
